# down-proj epilogue: residual X tiles prefetched 6 groups ahead with counted vmcnt, row-sumsq atomics deferred to epilogue end
# baseline (speedup 1.0000x reference)
; DI void ss_add(ssacc_t* p, float v) { atomicAdd(p, (ssacc_t)__float2ull_rn(v * 4294967296.f)); }
; DI float quad_sum(float s) { s += __shfl_xor(s, 16); s += __shfl_xor(s, 32); return s; }
; DI float sq8(const f32x4& a, const f32x4& b) { return (a[0] * a[0] + a[1] * a[1]) + (a[2] * a[2] + a[3] * a[3]) + (b[0] * b[0] + b[1] * b[1]) + (b[2] * b[2] + b[3] * b[3]); }
; DI u32x4 pack8(const f32x4& a, const f32x4& b) { u32x4 w; w.x = cvtpk(a[0], a[1]); w.y = cvtpk(a[2], a[3]); w.z = cvtpk(b[0], b[1]); w.w = cvtpk(b[2], b[3]); return w; }
;     DI void operator()(const Acc& acc, const Unit& u, int wr, int wc, int fr, int fq) const {
; #pragma unroll
;         for (int ai = 0; ai < 2; ++ai)
; #pragma unroll
;             for (int m = 0; m < 4; ++m) {
;                 asm volatile("" ::: "memory");
;                 const int row = u.pm * 256 + ai * 128 + wr * 64 + m * 16 + fr;
;                 float sq = 0.f;
; #pragma unroll
;                 for (int bj = 0; bj < 2; ++bj) {
;                     const size_t off = (size_t)row * 2048 + u.pn * 256 + bj * 128 + wc * 32 + 8 * fq;
;                     const f32x4 v0 = *(const f32x4*)(X + off) + acc[ai][bj][m][0], v1 = *(const f32x4*)(X + off + 4) + acc[ai][bj][m][1];
;                     *(f32x4*)(X + off) = v0; *(f32x4*)(X + off + 4) = v1; *(u32x4*)(XB + off) = pack8(v0, v1); sq += sq8(v0, v1);
;                 }
;                 sq = quad_sum(sq); if (fq == 0) ss_add(ssx + row, sq);
;             }
;     }
.LBB0_1567:
	v_lshl_add_u32 v144, s66, 8, v137
	s_lshl_b32 s4, s65, 8
	s_ashr_i32 s14, s4, 31
	v_ashrrev_i32_e32 v145, 31, v144
	v_mov_b32_e32 v143, s14
	v_or_b32_e32 v142, s4, v136
	v_lshlrev_b64 v[148:149], 11, v[144:145]
	v_lshl_add_u64 v[156:157], v[148:149], 0, v[142:143]
	v_lshl_add_u64 v[158:159], v[156:157], 2, s[44:45]
	v_mov_b32_e32 v190, v158
	v_mov_b32_e32 v191, v159
	global_load_dwordx4 v[160:163], v[158:159], off offset:16
	global_load_dwordx4 v[164:167], v[158:159], off
	s_mov_b64 s[100:101], 0x200
	v_lshl_add_u64 v[192:193], v[190:191], 0, s[100:101]
	global_load_dwordx4 v[168:171], v[192:193], off offset:16
	global_load_dwordx4 v[172:175], v[192:193], off
	s_mov_b64 s[100:101], 0x20000
	v_lshl_add_u64 v[192:193], v[190:191], 0, s[100:101]
	global_load_dwordx4 v[176:179], v[192:193], off offset:16
	global_load_dwordx4 v[180:183], v[192:193], off
	s_mov_b64 s[100:101], 0x20200
	v_lshl_add_u64 v[192:193], v[190:191], 0, s[100:101]
	global_load_dwordx4 v[208:211], v[192:193], off offset:16
	global_load_dwordx4 v[212:215], v[192:193], off
	s_mov_b64 s[100:101], 0x40000
	v_lshl_add_u64 v[192:193], v[190:191], 0, s[100:101]
	global_load_dwordx4 v[216:219], v[192:193], off offset:16
	global_load_dwordx4 v[220:223], v[192:193], off
	s_mov_b64 s[100:101], 0x40200
	v_lshl_add_u64 v[192:193], v[190:191], 0, s[100:101]
	global_load_dwordx4 v[224:227], v[192:193], off offset:16
	global_load_dwordx4 v[228:231], v[192:193], off
	s_waitcnt vmcnt(10)
	v_mov_b32_e32 v148, v160
	v_mov_b32_e32 v149, v161
	v_mov_b32_e32 v150, v162
	v_mov_b32_e32 v151, v163
	v_mov_b32_e32 v152, v164
	v_mov_b32_e32 v153, v165
	v_mov_b32_e32 v154, v166
	v_mov_b32_e32 v155, v167
	s_mov_b64 s[100:101], 0x60000
	v_lshl_add_u64 v[192:193], v[190:191], 0, s[100:101]
	global_load_dwordx4 v[160:163], v[192:193], off offset:16
	global_load_dwordx4 v[164:167], v[192:193], off
	v_pk_add_f32 v[126:127], v[126:127], v[150:151]
	v_pk_add_f32 v[122:123], v[122:123], v[154:155]
	v_pk_add_f32 v[120:121], v[120:121], v[152:153]
	v_pk_add_f32 v[124:125], v[124:125], v[148:149]
	global_store_dwordx4 v[158:159], v[120:123], off
	global_store_dwordx4 v[158:159], v[124:127], off offset:16
	v_cvt_pk_bf16_f32 v148, v120, v121
	v_mul_f32_e32 v121, v121, v121
	v_fmac_f32_e32 v121, v120, v120
	v_mul_f32_e32 v120, v123, v123
	v_fmac_f32_e32 v120, v122, v122
	v_add_f32_e32 v120, v121, v120
	v_mul_f32_e32 v121, v125, v125
	v_fmac_f32_e32 v121, v124, v124
	v_cvt_pk_bf16_f32 v149, v122, v123
	v_cvt_pk_bf16_f32 v150, v124, v125
	v_cvt_pk_bf16_f32 v151, v126, v127
	v_lshl_add_u64 v[152:153], v[156:157], 1, s[50:51]
	v_add_f32_e32 v120, v120, v121
	v_mul_f32_e32 v121, v127, v127
	v_or_b32_e32 v156, 0x80, v156
	global_store_dwordx4 v[152:153], v[148:151], off
	v_fmac_f32_e32 v121, v126, v126
	s_nop 0
	v_lshl_add_u64 v[148:149], v[156:157], 2, s[44:45]
	v_add_f32_e32 v150, v121, v120
	s_waitcnt vmcnt(13)
	v_mov_b32_e32 v120, v168
	v_mov_b32_e32 v121, v169
	v_mov_b32_e32 v122, v170
	v_mov_b32_e32 v123, v171
	v_mov_b32_e32 v124, v172
	v_mov_b32_e32 v125, v173
	v_mov_b32_e32 v126, v174
	v_mov_b32_e32 v127, v175
	s_mov_b64 s[100:101], 0x60200
	v_lshl_add_u64 v[192:193], v[190:191], 0, s[100:101]
	global_load_dwordx4 v[168:171], v[192:193], off offset:16
	global_load_dwordx4 v[172:175], v[192:193], off
	v_pk_add_f32 v[114:115], v[114:115], v[122:123]
	v_pk_add_f32 v[118:119], v[118:119], v[126:127]
	v_pk_add_f32 v[116:117], v[116:117], v[124:125]
	v_pk_add_f32 v[112:113], v[112:113], v[120:121]
	global_store_dwordx4 v[148:149], v[116:119], off
	global_store_dwordx4 v[148:149], v[112:115], off offset:16
	v_cvt_pk_bf16_f32 v120, v116, v117
	v_mul_f32_e32 v117, v117, v117
	v_fmac_f32_e32 v117, v116, v116
	v_mul_f32_e32 v116, v119, v119
	v_cvt_pk_bf16_f32 v122, v112, v113
	v_fmac_f32_e32 v116, v118, v118
	v_mul_f32_e32 v113, v113, v113
	v_add_f32_e32 v116, v117, v116
	v_fmac_f32_e32 v113, v112, v112
	v_add_f32_e32 v112, v116, v113
	v_mul_f32_e32 v113, v115, v115
	v_cvt_pk_bf16_f32 v123, v114, v115
	v_fmac_f32_e32 v113, v114, v114
	v_and_b32_e32 v114, 64, v199
	v_add_f32_e32 v112, v113, v112
	v_xor_b32_e32 v113, 16, v199
	v_add_u32_e32 v115, 64, v114
	v_cmp_lt_i32_e32 vcc, v113, v115
	v_add_f32_e32 v112, v150, v112
	v_cvt_pk_bf16_f32 v121, v118, v119
	v_cndmask_b32_e32 v113, v199, v113, vcc
	v_lshlrev_b32_e32 v116, 2, v113
	ds_bpermute_b32 v113, v116, v112
	v_lshl_add_u64 v[124:125], v[156:157], 1, s[50:51]
	global_store_dwordx4 v[124:125], v[120:123], off
	s_waitcnt lgkmcnt(0)
	v_add_f32_e32 v114, v112, v113
	v_xor_b32_e32 v112, 32, v199
	v_cmp_lt_i32_e32 vcc, v112, v115
	s_nop 1
	v_cndmask_b32_e32 v112, v199, v112, vcc
	v_lshlrev_b32_e32 v117, 2, v112
	ds_bpermute_b32 v115, v117, v114
	v_lshl_add_u64 v[112:113], v[144:145], 3, s[52:53]
	s_and_saveexec_b64 s[14:15], s[46:47]
	s_cbranch_execz .LBB0_1569
	s_waitcnt lgkmcnt(0)
	v_add_f32_e32 v114, v114, v115
	v_mul_f32_e32 v114, 0x4f800000, v114
	v_rndne_f32_e32 v114, v114
	v_mul_f32_e32 v115, 0x2f800000, v114
	v_floor_f32_e32 v115, v115
	v_fmac_f32_e32 v114, 0xcf800000, v115
	v_cvt_u32_f32_e32 v114, v114
	v_cvt_u32_f32_e32 v115, v115
	v_mov_b32_e32 v232, v114
	v_mov_b32_e32 v233, v115
; DI void ss_add(ssacc_t* p, float v) { atomicAdd(p, (ssacc_t)__float2ull_rn(v * 4294967296.f)); }
; DI float quad_sum(float s) { s += __shfl_xor(s, 16); s += __shfl_xor(s, 32); return s; }
; DI float sq8(const f32x4& a, const f32x4& b) { return (a[0] * a[0] + a[1] * a[1]) + (a[2] * a[2] + a[3] * a[3]) + (b[0] * b[0] + b[1] * b[1]) + (b[2] * b[2] + b[3] * b[3]); }
; DI u32x4 pack8(const f32x4& a, const f32x4& b) { u32x4 w; w.x = cvtpk(a[0], a[1]); w.y = cvtpk(a[2], a[3]); w.z = cvtpk(b[0], b[1]); w.w = cvtpk(b[2], b[3]); return w; }
;     DI void operator()(const Acc& acc, const Unit& u, int wr, int wc, int fr, int fq) const {
; #pragma unroll
;         for (int ai = 0; ai < 2; ++ai)
; #pragma unroll
;             for (int m = 0; m < 4; ++m) {
;                 asm volatile("" ::: "memory");
;                 const int row = u.pm * 256 + ai * 128 + wr * 64 + m * 16 + fr;
;                 float sq = 0.f;
; #pragma unroll
;                 for (int bj = 0; bj < 2; ++bj) {
;                     const size_t off = (size_t)row * 2048 + u.pn * 256 + bj * 128 + wc * 32 + 8 * fq;
;                     const f32x4 v0 = *(const f32x4*)(X + off) + acc[ai][bj][m][0], v1 = *(const f32x4*)(X + off + 4) + acc[ai][bj][m][1];
;                     *(f32x4*)(X + off) = v0; *(f32x4*)(X + off + 4) = v1; *(u32x4*)(XB + off) = pack8(v0, v1); sq += sq8(v0, v1);
;                 }
;                 sq = quad_sum(sq); if (fq == 0) ss_add(ssx + row, sq);
;             }
;     }
.LBB0_1569:
	s_or_b64 exec, exec, s[14:15]
	v_or_b32_e32 v114, 16, v144
	s_waitcnt lgkmcnt(0)
	v_ashrrev_i32_e32 v115, 31, v114
	v_lshlrev_b64 v[114:115], 11, v[114:115]
	v_lshl_add_u64 v[114:115], v[114:115], 0, v[142:143]
	v_lshl_add_u64 v[126:127], v[114:115], 2, s[44:45]
	s_waitcnt vmcnt(16)
	v_mov_b32_e32 v118, v176
	v_mov_b32_e32 v119, v177
	v_mov_b32_e32 v120, v178
	v_mov_b32_e32 v121, v179
	v_mov_b32_e32 v122, v180
	v_mov_b32_e32 v123, v181
	v_mov_b32_e32 v124, v182
	v_mov_b32_e32 v125, v183
	s_mov_b64 s[100:101], 0x100000
	v_lshl_add_u64 v[192:193], v[190:191], 0, s[100:101]
	global_load_dwordx4 v[176:179], v[192:193], off offset:16
	global_load_dwordx4 v[180:183], v[192:193], off
	v_pk_add_f32 v[106:107], v[106:107], v[120:121]
	v_pk_add_f32 v[110:111], v[110:111], v[124:125]
	v_pk_add_f32 v[108:109], v[108:109], v[122:123]
	v_pk_add_f32 v[104:105], v[104:105], v[118:119]
	global_store_dwordx4 v[126:127], v[108:111], off
	global_store_dwordx4 v[126:127], v[104:107], off offset:16
	v_cvt_pk_bf16_f32 v118, v108, v109
	v_mul_f32_e32 v109, v109, v109
	v_fmac_f32_e32 v109, v108, v108
	v_mul_f32_e32 v108, v111, v111
	v_cvt_pk_bf16_f32 v120, v104, v105
	v_fmac_f32_e32 v108, v110, v110
	v_mul_f32_e32 v105, v105, v105
	v_add_f32_e32 v108, v109, v108
	v_fmac_f32_e32 v105, v104, v104
	v_cvt_pk_bf16_f32 v119, v110, v111
	v_cvt_pk_bf16_f32 v121, v106, v107
	v_lshl_add_u64 v[122:123], v[114:115], 1, s[50:51]
	v_add_f32_e32 v104, v108, v105
	v_mul_f32_e32 v105, v107, v107
	v_or_b32_e32 v114, 0x80, v114
	global_store_dwordx4 v[122:123], v[118:121], off
	v_fmac_f32_e32 v105, v106, v106
	s_nop 0
	v_lshl_add_u64 v[118:119], v[114:115], 2, s[44:45]
	v_add_f32_e32 v120, v105, v104
	s_waitcnt vmcnt(19)
	v_mov_b32_e32 v104, v208
	v_mov_b32_e32 v105, v209
	v_mov_b32_e32 v106, v210
	v_mov_b32_e32 v107, v211
	v_mov_b32_e32 v108, v212
	v_mov_b32_e32 v109, v213
	v_mov_b32_e32 v110, v214
	v_mov_b32_e32 v111, v215
	s_mov_b64 s[100:101], 0x100200
	v_lshl_add_u64 v[192:193], v[190:191], 0, s[100:101]
	global_load_dwordx4 v[208:211], v[192:193], off offset:16
	global_load_dwordx4 v[212:215], v[192:193], off
	v_pk_add_f32 v[98:99], v[98:99], v[106:107]
	v_pk_add_f32 v[102:103], v[102:103], v[110:111]
	v_pk_add_f32 v[100:101], v[100:101], v[108:109]
	v_pk_add_f32 v[96:97], v[96:97], v[104:105]
	global_store_dwordx4 v[118:119], v[100:103], off
	global_store_dwordx4 v[118:119], v[96:99], off offset:16
	v_cvt_pk_bf16_f32 v104, v100, v101
	v_mul_f32_e32 v101, v101, v101
	v_fmac_f32_e32 v101, v100, v100
	v_mul_f32_e32 v100, v103, v103
	v_cvt_pk_bf16_f32 v106, v96, v97
	v_fmac_f32_e32 v100, v102, v102
	v_mul_f32_e32 v97, v97, v97
	v_add_f32_e32 v100, v101, v100
	v_fmac_f32_e32 v97, v96, v96
	v_add_f32_e32 v96, v100, v97
	v_mul_f32_e32 v97, v99, v99
	v_fmac_f32_e32 v97, v98, v98
	v_add_f32_e32 v96, v97, v96
	v_add_f32_e32 v96, v120, v96
	ds_bpermute_b32 v97, v116, v96
	v_cvt_pk_bf16_f32 v105, v102, v103
	v_cvt_pk_bf16_f32 v107, v98, v99
	v_lshl_add_u64 v[108:109], v[114:115], 1, s[50:51]
	global_store_dwordx4 v[108:109], v[104:107], off
	s_waitcnt lgkmcnt(0)
	v_add_f32_e32 v96, v96, v97
	ds_bpermute_b32 v97, v117, v96
	s_and_saveexec_b64 s[14:15], s[46:47]
	s_cbranch_execz .LBB0_1571
	s_waitcnt lgkmcnt(0)
	v_add_f32_e32 v96, v96, v97
	v_mul_f32_e32 v96, 0x4f800000, v96
	v_rndne_f32_e32 v96, v96
	v_mul_f32_e32 v97, 0x2f800000, v96
	v_floor_f32_e32 v97, v97
	v_fmac_f32_e32 v96, 0xcf800000, v97
	v_cvt_u32_f32_e32 v96, v96
	v_cvt_u32_f32_e32 v97, v97
	v_mov_b32_e32 v234, v96
	v_mov_b32_e32 v235, v97
.LBB0_1571:
	s_or_b64 exec, exec, s[14:15]
	v_or_b32_e32 v96, 32, v144
	s_waitcnt lgkmcnt(0)
	v_ashrrev_i32_e32 v97, 31, v96
	v_lshlrev_b64 v[96:97], 11, v[96:97]
	v_lshl_add_u64 v[96:97], v[96:97], 0, v[142:143]
	v_lshl_add_u64 v[106:107], v[96:97], 2, s[44:45]
	s_waitcnt vmcnt(22)
	v_mov_b32_e32 v98, v216
	v_mov_b32_e32 v99, v217
	v_mov_b32_e32 v100, v218
	v_mov_b32_e32 v101, v219
	v_mov_b32_e32 v102, v220
	v_mov_b32_e32 v103, v221
	v_mov_b32_e32 v104, v222
	v_mov_b32_e32 v105, v223
	s_mov_b64 s[100:101], 0x120000
	v_lshl_add_u64 v[192:193], v[190:191], 0, s[100:101]
	global_load_dwordx4 v[216:219], v[192:193], off offset:16
	global_load_dwordx4 v[220:223], v[192:193], off
	v_pk_add_f32 v[90:91], v[90:91], v[100:101]
	v_pk_add_f32 v[94:95], v[94:95], v[104:105]
	v_pk_add_f32 v[92:93], v[92:93], v[102:103]
	v_pk_add_f32 v[88:89], v[88:89], v[98:99]
	global_store_dwordx4 v[106:107], v[92:95], off
	global_store_dwordx4 v[106:107], v[88:91], off offset:16
	v_cvt_pk_bf16_f32 v98, v92, v93
	v_mul_f32_e32 v93, v93, v93
	v_fmac_f32_e32 v93, v92, v92
	v_mul_f32_e32 v92, v95, v95
	v_cvt_pk_bf16_f32 v100, v88, v89
	v_fmac_f32_e32 v92, v94, v94
	v_mul_f32_e32 v89, v89, v89
	v_add_f32_e32 v92, v93, v92
	v_fmac_f32_e32 v89, v88, v88
	v_cvt_pk_bf16_f32 v99, v94, v95
	v_cvt_pk_bf16_f32 v101, v90, v91
	v_lshl_add_u64 v[102:103], v[96:97], 1, s[50:51]
	v_add_f32_e32 v88, v92, v89
	v_mul_f32_e32 v89, v91, v91
	v_or_b32_e32 v96, 0x80, v96
	global_store_dwordx4 v[102:103], v[98:101], off
	v_fmac_f32_e32 v89, v90, v90
	s_nop 0
	v_lshl_add_u64 v[98:99], v[96:97], 2, s[44:45]
	v_add_f32_e32 v100, v89, v88
	s_waitcnt vmcnt(25)
	v_mov_b32_e32 v88, v224
	v_mov_b32_e32 v89, v225
	v_mov_b32_e32 v90, v226
	v_mov_b32_e32 v91, v227
	v_mov_b32_e32 v92, v228
	v_mov_b32_e32 v93, v229
	v_mov_b32_e32 v94, v230
	v_mov_b32_e32 v95, v231
	s_mov_b64 s[100:101], 0x120200
	v_lshl_add_u64 v[192:193], v[190:191], 0, s[100:101]
	global_load_dwordx4 v[224:227], v[192:193], off offset:16
	global_load_dwordx4 v[228:231], v[192:193], off
	v_pk_add_f32 v[82:83], v[82:83], v[90:91]
	v_pk_add_f32 v[86:87], v[86:87], v[94:95]
	v_pk_add_f32 v[84:85], v[84:85], v[92:93]
	v_pk_add_f32 v[80:81], v[80:81], v[88:89]
	global_store_dwordx4 v[98:99], v[84:87], off
	global_store_dwordx4 v[98:99], v[80:83], off offset:16
	v_cvt_pk_bf16_f32 v88, v84, v85
	v_mul_f32_e32 v85, v85, v85
	v_fmac_f32_e32 v85, v84, v84
	v_mul_f32_e32 v84, v87, v87
	v_cvt_pk_bf16_f32 v90, v80, v81
	v_fmac_f32_e32 v84, v86, v86
	v_mul_f32_e32 v81, v81, v81
	v_add_f32_e32 v84, v85, v84
	v_fmac_f32_e32 v81, v80, v80
	v_add_f32_e32 v80, v84, v81
	v_mul_f32_e32 v81, v83, v83
	v_fmac_f32_e32 v81, v82, v82
	v_add_f32_e32 v80, v81, v80
	v_add_f32_e32 v80, v100, v80
	ds_bpermute_b32 v81, v116, v80
	v_cvt_pk_bf16_f32 v89, v86, v87
	v_cvt_pk_bf16_f32 v91, v82, v83
	v_lshl_add_u64 v[92:93], v[96:97], 1, s[50:51]
	global_store_dwordx4 v[92:93], v[88:91], off
	s_waitcnt lgkmcnt(0)
	v_add_f32_e32 v80, v80, v81
	ds_bpermute_b32 v81, v117, v80
	s_and_saveexec_b64 s[14:15], s[46:47]
	s_cbranch_execz .LBB0_1573
	s_waitcnt lgkmcnt(0)
	v_add_f32_e32 v80, v80, v81
	v_mul_f32_e32 v80, 0x4f800000, v80
	v_rndne_f32_e32 v80, v80
	v_mul_f32_e32 v81, 0x2f800000, v80
	v_floor_f32_e32 v81, v81
	v_fmac_f32_e32 v80, 0xcf800000, v81
	v_cvt_u32_f32_e32 v80, v80
	v_cvt_u32_f32_e32 v81, v81
	v_mov_b32_e32 v236, v80
	v_mov_b32_e32 v237, v81
; DI void ss_add(ssacc_t* p, float v) { atomicAdd(p, (ssacc_t)__float2ull_rn(v * 4294967296.f)); }
; DI float quad_sum(float s) { s += __shfl_xor(s, 16); s += __shfl_xor(s, 32); return s; }
; DI float sq8(const f32x4& a, const f32x4& b) { return (a[0] * a[0] + a[1] * a[1]) + (a[2] * a[2] + a[3] * a[3]) + (b[0] * b[0] + b[1] * b[1]) + (b[2] * b[2] + b[3] * b[3]); }
; DI u32x4 pack8(const f32x4& a, const f32x4& b) { u32x4 w; w.x = cvtpk(a[0], a[1]); w.y = cvtpk(a[2], a[3]); w.z = cvtpk(b[0], b[1]); w.w = cvtpk(b[2], b[3]); return w; }
;     DI void operator()(const Acc& acc, const Unit& u, int wr, int wc, int fr, int fq) const {
; #pragma unroll
;         for (int ai = 0; ai < 2; ++ai)
; #pragma unroll
;             for (int m = 0; m < 4; ++m) {
;                 asm volatile("" ::: "memory");
;                 const int row = u.pm * 256 + ai * 128 + wr * 64 + m * 16 + fr;
;                 float sq = 0.f;
; #pragma unroll
;                 for (int bj = 0; bj < 2; ++bj) {
;                     const size_t off = (size_t)row * 2048 + u.pn * 256 + bj * 128 + wc * 32 + 8 * fq;
;                     const f32x4 v0 = *(const f32x4*)(X + off) + acc[ai][bj][m][0], v1 = *(const f32x4*)(X + off + 4) + acc[ai][bj][m][1];
;                     *(f32x4*)(X + off) = v0; *(f32x4*)(X + off + 4) = v1; *(u32x4*)(XB + off) = pack8(v0, v1); sq += sq8(v0, v1);
;                 }
;                 sq = quad_sum(sq); if (fq == 0) ss_add(ssx + row, sq);
;             }
;     }
.LBB0_1573:
	s_or_b64 exec, exec, s[14:15]
	v_or_b32_e32 v80, 48, v144
	s_waitcnt lgkmcnt(0)
	v_ashrrev_i32_e32 v81, 31, v80
	v_lshlrev_b64 v[80:81], 11, v[80:81]
	v_lshl_add_u64 v[80:81], v[80:81], 0, v[142:143]
	v_lshl_add_u64 v[90:91], v[80:81], 2, s[44:45]
	s_waitcnt vmcnt(28)
	v_mov_b32_e32 v82, v160
	v_mov_b32_e32 v83, v161
	v_mov_b32_e32 v84, v162
	v_mov_b32_e32 v85, v163
	v_mov_b32_e32 v86, v164
	v_mov_b32_e32 v87, v165
	v_mov_b32_e32 v88, v166
	v_mov_b32_e32 v89, v167
	s_mov_b64 s[100:101], 0x140000
	v_lshl_add_u64 v[192:193], v[190:191], 0, s[100:101]
	global_load_dwordx4 v[160:163], v[192:193], off offset:16
	global_load_dwordx4 v[164:167], v[192:193], off
	v_pk_add_f32 v[74:75], v[74:75], v[84:85]
	v_pk_add_f32 v[78:79], v[78:79], v[88:89]
	v_pk_add_f32 v[76:77], v[76:77], v[86:87]
	v_pk_add_f32 v[72:73], v[72:73], v[82:83]
	global_store_dwordx4 v[90:91], v[76:79], off
	global_store_dwordx4 v[90:91], v[72:75], off offset:16
	v_cvt_pk_bf16_f32 v82, v76, v77
	v_mul_f32_e32 v77, v77, v77
	v_fmac_f32_e32 v77, v76, v76
	v_mul_f32_e32 v76, v79, v79
	v_cvt_pk_bf16_f32 v84, v72, v73
	v_fmac_f32_e32 v76, v78, v78
	v_mul_f32_e32 v73, v73, v73
	v_add_f32_e32 v76, v77, v76
	v_fmac_f32_e32 v73, v72, v72
	v_cvt_pk_bf16_f32 v83, v78, v79
	v_cvt_pk_bf16_f32 v85, v74, v75
	v_lshl_add_u64 v[86:87], v[80:81], 1, s[50:51]
	v_add_f32_e32 v72, v76, v73
	v_mul_f32_e32 v73, v75, v75
	v_or_b32_e32 v80, 0x80, v80
	global_store_dwordx4 v[86:87], v[82:85], off
	v_fmac_f32_e32 v73, v74, v74
	s_nop 0
	v_lshl_add_u64 v[82:83], v[80:81], 2, s[44:45]
	v_add_f32_e32 v84, v73, v72
	s_waitcnt vmcnt(28)
	v_mov_b32_e32 v72, v168
	v_mov_b32_e32 v73, v169
	v_mov_b32_e32 v74, v170
	v_mov_b32_e32 v75, v171
	v_mov_b32_e32 v76, v172
	v_mov_b32_e32 v77, v173
	v_mov_b32_e32 v78, v174
	v_mov_b32_e32 v79, v175
	s_mov_b64 s[100:101], 0x140200
	v_lshl_add_u64 v[192:193], v[190:191], 0, s[100:101]
	global_load_dwordx4 v[168:171], v[192:193], off offset:16
	global_load_dwordx4 v[172:175], v[192:193], off
	v_pk_add_f32 v[66:67], v[66:67], v[74:75]
	v_pk_add_f32 v[70:71], v[70:71], v[78:79]
	v_pk_add_f32 v[68:69], v[68:69], v[76:77]
	v_pk_add_f32 v[64:65], v[64:65], v[72:73]
	global_store_dwordx4 v[82:83], v[68:71], off
	global_store_dwordx4 v[82:83], v[64:67], off offset:16
	v_cvt_pk_bf16_f32 v72, v68, v69
	v_mul_f32_e32 v69, v69, v69
	v_fmac_f32_e32 v69, v68, v68
	v_mul_f32_e32 v68, v71, v71
	v_cvt_pk_bf16_f32 v74, v64, v65
	v_fmac_f32_e32 v68, v70, v70
	v_mul_f32_e32 v65, v65, v65
	v_add_f32_e32 v68, v69, v68
	v_fmac_f32_e32 v65, v64, v64
	v_add_f32_e32 v64, v68, v65
	v_mul_f32_e32 v65, v67, v67
	v_fmac_f32_e32 v65, v66, v66
	v_add_f32_e32 v64, v65, v64
	v_add_f32_e32 v64, v84, v64
	ds_bpermute_b32 v65, v116, v64
	v_cvt_pk_bf16_f32 v73, v70, v71
	v_cvt_pk_bf16_f32 v75, v66, v67
	v_lshl_add_u64 v[76:77], v[80:81], 1, s[50:51]
	global_store_dwordx4 v[76:77], v[72:75], off
	s_waitcnt lgkmcnt(0)
	v_add_f32_e32 v64, v64, v65
	ds_bpermute_b32 v65, v117, v64
	s_and_saveexec_b64 s[14:15], s[46:47]
	s_cbranch_execz .LBB0_1575
	s_waitcnt lgkmcnt(0)
	v_add_f32_e32 v64, v64, v65
	v_mul_f32_e32 v64, 0x4f800000, v64
	v_rndne_f32_e32 v64, v64
	v_mul_f32_e32 v65, 0x2f800000, v64
	v_floor_f32_e32 v65, v65
	v_fmac_f32_e32 v64, 0xcf800000, v65
	v_cvt_u32_f32_e32 v64, v64
	v_cvt_u32_f32_e32 v65, v65
	v_mov_b32_e32 v238, v64
	v_mov_b32_e32 v239, v65
.LBB0_1575:
	s_or_b64 exec, exec, s[14:15]
	v_add_u32_e32 v64, 0x80, v144
	s_waitcnt lgkmcnt(0)
	v_ashrrev_i32_e32 v65, 31, v64
	v_lshlrev_b64 v[64:65], 11, v[64:65]
	v_lshl_add_u64 v[64:65], v[64:65], 0, v[142:143]
	v_lshl_add_u64 v[74:75], v[64:65], 2, s[44:45]
	s_waitcnt vmcnt(28)
	v_mov_b32_e32 v66, v176
	v_mov_b32_e32 v67, v177
	v_mov_b32_e32 v68, v178
	v_mov_b32_e32 v69, v179
	v_mov_b32_e32 v70, v180
	v_mov_b32_e32 v71, v181
	v_mov_b32_e32 v72, v182
	v_mov_b32_e32 v73, v183
	s_mov_b64 s[100:101], 0x160000
	v_lshl_add_u64 v[192:193], v[190:191], 0, s[100:101]
	global_load_dwordx4 v[176:179], v[192:193], off offset:16
	global_load_dwordx4 v[180:183], v[192:193], off
	v_pk_add_f32 v[58:59], v[58:59], v[68:69]
	v_pk_add_f32 v[62:63], v[62:63], v[72:73]
	v_pk_add_f32 v[60:61], v[60:61], v[70:71]
	v_pk_add_f32 v[56:57], v[56:57], v[66:67]
	global_store_dwordx4 v[74:75], v[60:63], off
	global_store_dwordx4 v[74:75], v[56:59], off offset:16
	v_cvt_pk_bf16_f32 v66, v60, v61
	v_mul_f32_e32 v61, v61, v61
	v_fmac_f32_e32 v61, v60, v60
	v_mul_f32_e32 v60, v63, v63
	v_cvt_pk_bf16_f32 v68, v56, v57
	v_fmac_f32_e32 v60, v62, v62
	v_mul_f32_e32 v57, v57, v57
	v_add_f32_e32 v60, v61, v60
	v_fmac_f32_e32 v57, v56, v56
	v_cvt_pk_bf16_f32 v67, v62, v63
	v_cvt_pk_bf16_f32 v69, v58, v59
	v_lshl_add_u64 v[70:71], v[64:65], 1, s[50:51]
	v_add_f32_e32 v56, v60, v57
	v_mul_f32_e32 v57, v59, v59
	v_or_b32_e32 v64, 0x80, v64
	global_store_dwordx4 v[70:71], v[66:69], off
	v_fmac_f32_e32 v57, v58, v58
	s_nop 0
	v_lshl_add_u64 v[66:67], v[64:65], 2, s[44:45]
	v_add_f32_e32 v68, v57, v56
	s_waitcnt vmcnt(28)
	v_mov_b32_e32 v56, v208
	v_mov_b32_e32 v57, v209
	v_mov_b32_e32 v58, v210
	v_mov_b32_e32 v59, v211
	v_mov_b32_e32 v60, v212
	v_mov_b32_e32 v61, v213
	v_mov_b32_e32 v62, v214
	v_mov_b32_e32 v63, v215
	s_mov_b64 s[100:101], 0x160200
	v_lshl_add_u64 v[192:193], v[190:191], 0, s[100:101]
	global_load_dwordx4 v[208:211], v[192:193], off offset:16
	global_load_dwordx4 v[212:215], v[192:193], off
	v_pk_add_f32 v[50:51], v[50:51], v[58:59]
	v_pk_add_f32 v[54:55], v[54:55], v[62:63]
	v_pk_add_f32 v[52:53], v[52:53], v[60:61]
	v_pk_add_f32 v[48:49], v[48:49], v[56:57]
	global_store_dwordx4 v[66:67], v[52:55], off
	global_store_dwordx4 v[66:67], v[48:51], off offset:16
	v_cvt_pk_bf16_f32 v56, v52, v53
	v_mul_f32_e32 v53, v53, v53
	v_fmac_f32_e32 v53, v52, v52
	v_mul_f32_e32 v52, v55, v55
	v_cvt_pk_bf16_f32 v58, v48, v49
	v_fmac_f32_e32 v52, v54, v54
	v_mul_f32_e32 v49, v49, v49
	v_add_f32_e32 v52, v53, v52
	v_fmac_f32_e32 v49, v48, v48
	v_add_f32_e32 v48, v52, v49
	v_mul_f32_e32 v49, v51, v51
	v_fmac_f32_e32 v49, v50, v50
	v_add_f32_e32 v48, v49, v48
	v_add_f32_e32 v48, v68, v48
	ds_bpermute_b32 v49, v116, v48
	v_cvt_pk_bf16_f32 v57, v54, v55
	v_cvt_pk_bf16_f32 v59, v50, v51
	v_lshl_add_u64 v[60:61], v[64:65], 1, s[50:51]
	global_store_dwordx4 v[60:61], v[56:59], off
	s_waitcnt lgkmcnt(0)
	v_add_f32_e32 v48, v48, v49
	ds_bpermute_b32 v49, v117, v48
	s_and_saveexec_b64 s[14:15], s[46:47]
	s_cbranch_execz .LBB0_1577
	s_waitcnt lgkmcnt(0)
	v_add_f32_e32 v48, v48, v49
	v_mul_f32_e32 v48, 0x4f800000, v48
	v_rndne_f32_e32 v48, v48
	v_mul_f32_e32 v49, 0x2f800000, v48
	v_floor_f32_e32 v49, v49
	v_fmac_f32_e32 v48, 0xcf800000, v49
	v_cvt_u32_f32_e32 v48, v48
	v_cvt_u32_f32_e32 v49, v49
	v_mov_b32_e32 v240, v48
	v_mov_b32_e32 v241, v49
; DI void ss_add(ssacc_t* p, float v) { atomicAdd(p, (ssacc_t)__float2ull_rn(v * 4294967296.f)); }
; DI float quad_sum(float s) { s += __shfl_xor(s, 16); s += __shfl_xor(s, 32); return s; }
; DI float sq8(const f32x4& a, const f32x4& b) { return (a[0] * a[0] + a[1] * a[1]) + (a[2] * a[2] + a[3] * a[3]) + (b[0] * b[0] + b[1] * b[1]) + (b[2] * b[2] + b[3] * b[3]); }
; DI u32x4 pack8(const f32x4& a, const f32x4& b) { u32x4 w; w.x = cvtpk(a[0], a[1]); w.y = cvtpk(a[2], a[3]); w.z = cvtpk(b[0], b[1]); w.w = cvtpk(b[2], b[3]); return w; }
;     DI void operator()(const Acc& acc, const Unit& u, int wr, int wc, int fr, int fq) const {
; #pragma unroll
;         for (int ai = 0; ai < 2; ++ai)
; #pragma unroll
;             for (int m = 0; m < 4; ++m) {
;                 asm volatile("" ::: "memory");
;                 const int row = u.pm * 256 + ai * 128 + wr * 64 + m * 16 + fr;
;                 float sq = 0.f;
; #pragma unroll
;                 for (int bj = 0; bj < 2; ++bj) {
;                     const size_t off = (size_t)row * 2048 + u.pn * 256 + bj * 128 + wc * 32 + 8 * fq;
;                     const f32x4 v0 = *(const f32x4*)(X + off) + acc[ai][bj][m][0], v1 = *(const f32x4*)(X + off + 4) + acc[ai][bj][m][1];
;                     *(f32x4*)(X + off) = v0; *(f32x4*)(X + off + 4) = v1; *(u32x4*)(XB + off) = pack8(v0, v1); sq += sq8(v0, v1);
;                 }
;                 sq = quad_sum(sq); if (fq == 0) ss_add(ssx + row, sq);
;             }
;     }
.LBB0_1577:
	s_or_b64 exec, exec, s[14:15]
	v_add_u32_e32 v48, 0x90, v144
	s_waitcnt lgkmcnt(0)
	v_ashrrev_i32_e32 v49, 31, v48
	v_lshlrev_b64 v[48:49], 11, v[48:49]
	v_lshl_add_u64 v[48:49], v[48:49], 0, v[142:143]
	v_lshl_add_u64 v[58:59], v[48:49], 2, s[44:45]
	s_waitcnt vmcnt(28)
	v_mov_b32_e32 v50, v216
	v_mov_b32_e32 v51, v217
	v_mov_b32_e32 v52, v218
	v_mov_b32_e32 v53, v219
	v_mov_b32_e32 v54, v220
	v_mov_b32_e32 v55, v221
	v_mov_b32_e32 v56, v222
	v_mov_b32_e32 v57, v223
	v_pk_add_f32 v[42:43], v[42:43], v[52:53]
	v_pk_add_f32 v[46:47], v[46:47], v[56:57]
	v_pk_add_f32 v[44:45], v[44:45], v[54:55]
	v_pk_add_f32 v[40:41], v[40:41], v[50:51]
	global_store_dwordx4 v[58:59], v[44:47], off
	global_store_dwordx4 v[58:59], v[40:43], off offset:16
	v_cvt_pk_bf16_f32 v50, v44, v45
	v_mul_f32_e32 v45, v45, v45
	v_fmac_f32_e32 v45, v44, v44
	v_mul_f32_e32 v44, v47, v47
	v_cvt_pk_bf16_f32 v52, v40, v41
	v_fmac_f32_e32 v44, v46, v46
	v_mul_f32_e32 v41, v41, v41
	v_add_f32_e32 v44, v45, v44
	v_fmac_f32_e32 v41, v40, v40
	v_cvt_pk_bf16_f32 v51, v46, v47
	v_cvt_pk_bf16_f32 v53, v42, v43
	v_lshl_add_u64 v[54:55], v[48:49], 1, s[50:51]
	v_add_f32_e32 v40, v44, v41
	v_mul_f32_e32 v41, v43, v43
	v_or_b32_e32 v48, 0x80, v48
	global_store_dwordx4 v[54:55], v[50:53], off
	v_fmac_f32_e32 v41, v42, v42
	s_nop 0
	v_lshl_add_u64 v[50:51], v[48:49], 2, s[44:45]
	v_add_f32_e32 v52, v41, v40
	s_waitcnt vmcnt(26)
	v_mov_b32_e32 v40, v224
	v_mov_b32_e32 v41, v225
	v_mov_b32_e32 v42, v226
	v_mov_b32_e32 v43, v227
	v_mov_b32_e32 v44, v228
	v_mov_b32_e32 v45, v229
	v_mov_b32_e32 v46, v230
	v_mov_b32_e32 v47, v231
	v_pk_add_f32 v[34:35], v[34:35], v[42:43]
	v_pk_add_f32 v[38:39], v[38:39], v[46:47]
	v_pk_add_f32 v[36:37], v[36:37], v[44:45]
	v_pk_add_f32 v[32:33], v[32:33], v[40:41]
	global_store_dwordx4 v[50:51], v[36:39], off
	global_store_dwordx4 v[50:51], v[32:35], off offset:16
	v_cvt_pk_bf16_f32 v40, v36, v37
	v_mul_f32_e32 v37, v37, v37
	v_fmac_f32_e32 v37, v36, v36
	v_mul_f32_e32 v36, v39, v39
	v_cvt_pk_bf16_f32 v42, v32, v33
	v_fmac_f32_e32 v36, v38, v38
	v_mul_f32_e32 v33, v33, v33
	v_add_f32_e32 v36, v37, v36
	v_fmac_f32_e32 v33, v32, v32
	v_add_f32_e32 v32, v36, v33
	v_mul_f32_e32 v33, v35, v35
	v_fmac_f32_e32 v33, v34, v34
	v_add_f32_e32 v32, v33, v32
	v_add_f32_e32 v32, v52, v32
	ds_bpermute_b32 v33, v116, v32
	v_cvt_pk_bf16_f32 v41, v38, v39
	v_cvt_pk_bf16_f32 v43, v34, v35
	v_lshl_add_u64 v[44:45], v[48:49], 1, s[50:51]
	global_store_dwordx4 v[44:45], v[40:43], off
	s_waitcnt lgkmcnt(0)
	v_add_f32_e32 v32, v32, v33
	ds_bpermute_b32 v33, v117, v32
	s_and_saveexec_b64 s[14:15], s[46:47]
	s_cbranch_execz .LBB0_1579
	s_waitcnt lgkmcnt(0)
	v_add_f32_e32 v32, v32, v33
	v_mul_f32_e32 v32, 0x4f800000, v32
	v_rndne_f32_e32 v32, v32
	v_mul_f32_e32 v33, 0x2f800000, v32
	v_floor_f32_e32 v33, v33
	v_fmac_f32_e32 v32, 0xcf800000, v33
	v_cvt_u32_f32_e32 v32, v32
	v_cvt_u32_f32_e32 v33, v33
	v_mov_b32_e32 v242, v32
	v_mov_b32_e32 v243, v33
.LBB0_1579:
	s_or_b64 exec, exec, s[14:15]
	v_add_u32_e32 v32, 0xa0, v144
	s_waitcnt lgkmcnt(0)
	v_ashrrev_i32_e32 v33, 31, v32
	v_lshlrev_b64 v[32:33], 11, v[32:33]
	v_lshl_add_u64 v[32:33], v[32:33], 0, v[142:143]
	v_lshl_add_u64 v[42:43], v[32:33], 2, s[44:45]
	s_waitcnt vmcnt(24)
	v_mov_b32_e32 v34, v160
	v_mov_b32_e32 v35, v161
	v_mov_b32_e32 v36, v162
	v_mov_b32_e32 v37, v163
	v_mov_b32_e32 v38, v164
	v_mov_b32_e32 v39, v165
	v_mov_b32_e32 v40, v166
	v_mov_b32_e32 v41, v167
	v_pk_add_f32 v[26:27], v[26:27], v[36:37]
	v_pk_add_f32 v[30:31], v[30:31], v[40:41]
	v_pk_add_f32 v[28:29], v[28:29], v[38:39]
	v_pk_add_f32 v[24:25], v[24:25], v[34:35]
	global_store_dwordx4 v[42:43], v[28:31], off
	global_store_dwordx4 v[42:43], v[24:27], off offset:16
	v_cvt_pk_bf16_f32 v34, v28, v29
	v_mul_f32_e32 v29, v29, v29
	v_fmac_f32_e32 v29, v28, v28
	v_mul_f32_e32 v28, v31, v31
	v_cvt_pk_bf16_f32 v36, v24, v25
	v_fmac_f32_e32 v28, v30, v30
	v_mul_f32_e32 v25, v25, v25
	v_add_f32_e32 v28, v29, v28
	v_fmac_f32_e32 v25, v24, v24
	v_cvt_pk_bf16_f32 v35, v30, v31
	v_cvt_pk_bf16_f32 v37, v26, v27
	v_lshl_add_u64 v[38:39], v[32:33], 1, s[50:51]
	v_add_f32_e32 v24, v28, v25
	v_mul_f32_e32 v25, v27, v27
	v_or_b32_e32 v32, 0x80, v32
	global_store_dwordx4 v[38:39], v[34:37], off
	v_fmac_f32_e32 v25, v26, v26
	s_nop 0
	v_lshl_add_u64 v[34:35], v[32:33], 2, s[44:45]
	v_add_f32_e32 v36, v25, v24
	s_waitcnt vmcnt(22)
	v_mov_b32_e32 v24, v168
	v_mov_b32_e32 v25, v169
	v_mov_b32_e32 v26, v170
	v_mov_b32_e32 v27, v171
	v_mov_b32_e32 v28, v172
	v_mov_b32_e32 v29, v173
	v_mov_b32_e32 v30, v174
	v_mov_b32_e32 v31, v175
	v_pk_add_f32 v[18:19], v[18:19], v[26:27]
	v_pk_add_f32 v[22:23], v[22:23], v[30:31]
	v_pk_add_f32 v[20:21], v[20:21], v[28:29]
	v_pk_add_f32 v[16:17], v[16:17], v[24:25]
	global_store_dwordx4 v[34:35], v[20:23], off
	global_store_dwordx4 v[34:35], v[16:19], off offset:16
	v_cvt_pk_bf16_f32 v24, v20, v21
	v_mul_f32_e32 v21, v21, v21
	v_fmac_f32_e32 v21, v20, v20
	v_mul_f32_e32 v20, v23, v23
	v_cvt_pk_bf16_f32 v26, v16, v17
	v_fmac_f32_e32 v20, v22, v22
	v_mul_f32_e32 v17, v17, v17
	v_add_f32_e32 v20, v21, v20
	v_fmac_f32_e32 v17, v16, v16
	v_add_f32_e32 v16, v20, v17
	v_mul_f32_e32 v17, v19, v19
	v_fmac_f32_e32 v17, v18, v18
	v_add_f32_e32 v16, v17, v16
	v_add_f32_e32 v16, v36, v16
	ds_bpermute_b32 v17, v116, v16
	v_cvt_pk_bf16_f32 v25, v22, v23
	v_cvt_pk_bf16_f32 v27, v18, v19
	v_lshl_add_u64 v[28:29], v[32:33], 1, s[50:51]
	global_store_dwordx4 v[28:29], v[24:27], off
	s_waitcnt lgkmcnt(0)
	v_add_f32_e32 v16, v16, v17
	ds_bpermute_b32 v17, v117, v16
	s_and_saveexec_b64 s[14:15], s[46:47]
	s_cbranch_execz .LBB0_1581
	s_waitcnt lgkmcnt(0)
	v_add_f32_e32 v16, v16, v17
	v_mul_f32_e32 v16, 0x4f800000, v16
	v_rndne_f32_e32 v16, v16
	v_mul_f32_e32 v17, 0x2f800000, v16
	v_floor_f32_e32 v17, v17
	v_fmac_f32_e32 v16, 0xcf800000, v17
	v_cvt_u32_f32_e32 v16, v16
	v_cvt_u32_f32_e32 v17, v17
	v_mov_b32_e32 v244, v16
	v_mov_b32_e32 v245, v17
; DI void ss_add(ssacc_t* p, float v) { atomicAdd(p, (ssacc_t)__float2ull_rn(v * 4294967296.f)); }
; DI float quad_sum(float s) { s += __shfl_xor(s, 16); s += __shfl_xor(s, 32); return s; }
; DI float sq8(const f32x4& a, const f32x4& b) { return (a[0] * a[0] + a[1] * a[1]) + (a[2] * a[2] + a[3] * a[3]) + (b[0] * b[0] + b[1] * b[1]) + (b[2] * b[2] + b[3] * b[3]); }
; DI u32x4 pack8(const f32x4& a, const f32x4& b) { u32x4 w; w.x = cvtpk(a[0], a[1]); w.y = cvtpk(a[2], a[3]); w.z = cvtpk(b[0], b[1]); w.w = cvtpk(b[2], b[3]); return w; }
;     DI void operator()(const Acc& acc, const Unit& u, int wr, int wc, int fr, int fq) const {
; #pragma unroll
;         for (int ai = 0; ai < 2; ++ai)
; #pragma unroll
;             for (int m = 0; m < 4; ++m) {
;                 asm volatile("" ::: "memory");
;                 const int row = u.pm * 256 + ai * 128 + wr * 64 + m * 16 + fr;
;                 float sq = 0.f;
; #pragma unroll
;                 for (int bj = 0; bj < 2; ++bj) {
;                     const size_t off = (size_t)row * 2048 + u.pn * 256 + bj * 128 + wc * 32 + 8 * fq;
;                     const f32x4 v0 = *(const f32x4*)(X + off) + acc[ai][bj][m][0], v1 = *(const f32x4*)(X + off + 4) + acc[ai][bj][m][1];
;                     *(f32x4*)(X + off) = v0; *(f32x4*)(X + off + 4) = v1; *(u32x4*)(XB + off) = pack8(v0, v1); sq += sq8(v0, v1);
;                 }
;                 sq = quad_sum(sq); if (fq == 0) ss_add(ssx + row, sq);
;             }
;     }
.LBB0_1581:
	s_or_b64 exec, exec, s[14:15]
	v_add_u32_e32 v16, 0xb0, v144
	s_waitcnt lgkmcnt(0)
	v_ashrrev_i32_e32 v17, 31, v16
	v_lshlrev_b64 v[16:17], 11, v[16:17]
	v_lshl_add_u64 v[16:17], v[16:17], 0, v[142:143]
	v_lshl_add_u64 v[26:27], v[16:17], 2, s[44:45]
	s_waitcnt vmcnt(20)
	v_mov_b32_e32 v18, v176
	v_mov_b32_e32 v19, v177
	v_mov_b32_e32 v20, v178
	v_mov_b32_e32 v21, v179
	v_mov_b32_e32 v22, v180
	v_mov_b32_e32 v23, v181
	v_mov_b32_e32 v24, v182
	v_mov_b32_e32 v25, v183
	v_pk_add_f32 v[10:11], v[10:11], v[20:21]
	v_pk_add_f32 v[14:15], v[14:15], v[24:25]
	v_pk_add_f32 v[12:13], v[12:13], v[22:23]
	v_pk_add_f32 v[8:9], v[8:9], v[18:19]
	global_store_dwordx4 v[26:27], v[12:15], off
	global_store_dwordx4 v[26:27], v[8:11], off offset:16
	v_cvt_pk_bf16_f32 v18, v12, v13
	v_mul_f32_e32 v13, v13, v13
	v_fmac_f32_e32 v13, v12, v12
	v_mul_f32_e32 v12, v15, v15
	v_cvt_pk_bf16_f32 v20, v8, v9
	v_fmac_f32_e32 v12, v14, v14
	v_mul_f32_e32 v9, v9, v9
	v_add_f32_e32 v12, v13, v12
	v_fmac_f32_e32 v9, v8, v8
	v_cvt_pk_bf16_f32 v19, v14, v15
	v_cvt_pk_bf16_f32 v21, v10, v11
	v_lshl_add_u64 v[22:23], v[16:17], 1, s[50:51]
	v_add_f32_e32 v8, v12, v9
	v_mul_f32_e32 v9, v11, v11
	v_or_b32_e32 v16, 0x80, v16
	global_store_dwordx4 v[22:23], v[18:21], off
	v_fmac_f32_e32 v9, v10, v10
	s_nop 0
	v_lshl_add_u64 v[18:19], v[16:17], 2, s[44:45]
	v_add_f32_e32 v20, v9, v8
	s_waitcnt vmcnt(18)
	v_mov_b32_e32 v8, v208
	v_mov_b32_e32 v9, v209
	v_mov_b32_e32 v10, v210
	v_mov_b32_e32 v11, v211
	v_mov_b32_e32 v12, v212
	v_mov_b32_e32 v13, v213
	v_mov_b32_e32 v14, v214
	v_mov_b32_e32 v15, v215
	v_pk_add_f32 v[2:3], v[2:3], v[10:11]
	v_pk_add_f32 v[6:7], v[6:7], v[14:15]
	v_pk_add_f32 v[4:5], v[4:5], v[12:13]
	v_pk_add_f32 v[0:1], v[0:1], v[8:9]
	global_store_dwordx4 v[18:19], v[4:7], off
	global_store_dwordx4 v[18:19], v[0:3], off offset:16
	v_cvt_pk_bf16_f32 v8, v4, v5
	v_mul_f32_e32 v5, v5, v5
	v_fmac_f32_e32 v5, v4, v4
	v_mul_f32_e32 v4, v7, v7
	v_cvt_pk_bf16_f32 v10, v0, v1
	v_fmac_f32_e32 v4, v6, v6
	v_mul_f32_e32 v1, v1, v1
	v_add_f32_e32 v4, v5, v4
	v_fmac_f32_e32 v1, v0, v0
	v_add_f32_e32 v0, v4, v1
	v_mul_f32_e32 v1, v3, v3
	v_fmac_f32_e32 v1, v2, v2
	v_add_f32_e32 v0, v1, v0
	v_add_f32_e32 v0, v20, v0
	ds_bpermute_b32 v1, v116, v0
	v_cvt_pk_bf16_f32 v9, v6, v7
	v_cvt_pk_bf16_f32 v11, v2, v3
	v_lshl_add_u64 v[12:13], v[16:17], 1, s[50:51]
	global_store_dwordx4 v[12:13], v[8:11], off
	s_waitcnt lgkmcnt(0)
	v_add_f32_e32 v0, v0, v1
	ds_bpermute_b32 v1, v117, v0
	s_and_saveexec_b64 s[14:15], s[46:47]
	s_cbranch_execz .LBB0_1583
	s_waitcnt lgkmcnt(0)
	v_add_f32_e32 v0, v0, v1
	v_mul_f32_e32 v0, 0x4f800000, v0
	v_rndne_f32_e32 v0, v0
	v_mul_f32_e32 v1, 0x2f800000, v0
	v_floor_f32_e32 v1, v1
	v_fmac_f32_e32 v0, 0xcf800000, v1
	v_cvt_u32_f32_e32 v0, v0
	v_cvt_u32_f32_e32 v1, v1
	global_atomic_add_x2 v[112:113], v[232:233], off
	global_atomic_add_x2 v[112:113], v[234:235], off offset:128
	global_atomic_add_x2 v[112:113], v[236:237], off offset:256
	global_atomic_add_x2 v[112:113], v[238:239], off offset:384
	global_atomic_add_x2 v[112:113], v[240:241], off offset:1024
	global_atomic_add_x2 v[112:113], v[242:243], off offset:1152
	global_atomic_add_x2 v[112:113], v[244:245], off offset:1280
	global_atomic_add_x2 v[112:113], v[0:1], off offset:1408

; __global__ void __launch_bounds__(512, 2) hymba_fwd(Params p_unused) {
	.amdhsa_kernel _Z9hymba_fwd6Params
		.amdhsa_group_segment_fixed_size 0
		.amdhsa_private_segment_fixed_size 0
		.amdhsa_kernarg_size 480
		.amdhsa_user_sgpr_count 2
		.amdhsa_user_sgpr_dispatch_ptr 0
		.amdhsa_user_sgpr_queue_ptr 0
		.amdhsa_user_sgpr_kernarg_segment_ptr 1
		.amdhsa_user_sgpr_dispatch_id 0
		.amdhsa_user_sgpr_kernarg_preload_length 0
		.amdhsa_user_sgpr_kernarg_preload_offset 0
		.amdhsa_user_sgpr_private_segment_size 0
		.amdhsa_uses_dynamic_stack 0
		.amdhsa_enable_private_segment 0
		.amdhsa_system_sgpr_workgroup_id_x 1
		.amdhsa_system_sgpr_workgroup_id_y 0
		.amdhsa_system_sgpr_workgroup_id_z 0
		.amdhsa_system_sgpr_workgroup_info 0
		.amdhsa_system_vgpr_workitem_id 2
		.amdhsa_next_free_vgpr 256
		.amdhsa_next_free_sgpr 102
		.amdhsa_accum_offset 256
		.amdhsa_reserve_vcc 1
		.amdhsa_float_round_mode_32 0
		.amdhsa_float_round_mode_16_64 0
		.amdhsa_float_denorm_mode_32 3
		.amdhsa_float_denorm_mode_16_64 3
		.amdhsa_dx10_clamp 1
		.amdhsa_ieee_mode 1
		.amdhsa_fp16_overflow 0
		.amdhsa_tg_split 0
		.amdhsa_exception_fp_ieee_invalid_op 0
		.amdhsa_exception_fp_denorm_src 0
		.amdhsa_exception_fp_ieee_div_zero 0
		.amdhsa_exception_fp_ieee_overflow 0
		.amdhsa_exception_fp_ieee_underflow 0
		.amdhsa_exception_fp_ieee_inexact 0
		.amdhsa_exception_int_div_zero 0
	.end_amdhsa_kernel

; __global__ void __launch_bounds__(512, 2) hymba_fwd(Params p_unused) {
amdhsa.kernels:
  - .agpr_count:     0
    .args:
      - .offset:         0
        .size:           224
        .value_kind:     by_value
      - .offset:         224
        .size:           4
        .value_kind:     hidden_block_count_x
      - .offset:         228
        .size:           4
        .value_kind:     hidden_block_count_y
      - .offset:         232
        .size:           4
        .value_kind:     hidden_block_count_z
      - .offset:         236
        .size:           2
        .value_kind:     hidden_group_size_x
      - .offset:         238
        .size:           2
        .value_kind:     hidden_group_size_y
      - .offset:         240
        .size:           2
        .value_kind:     hidden_group_size_z
      - .offset:         242
        .size:           2
        .value_kind:     hidden_remainder_x
      - .offset:         244
        .size:           2
        .value_kind:     hidden_remainder_y
      - .offset:         246
        .size:           2
        .value_kind:     hidden_remainder_z
      - .offset:         264
        .size:           8
        .value_kind:     hidden_global_offset_x
      - .offset:         272
        .size:           8
        .value_kind:     hidden_global_offset_y
      - .offset:         280
        .size:           8
        .value_kind:     hidden_global_offset_z
      - .offset:         288
        .size:           2
        .value_kind:     hidden_grid_dims
      - .offset:         312
        .size:           8
        .value_kind:     hidden_multigrid_sync_arg
      - .offset:         344
        .size:           4
        .value_kind:     hidden_dynamic_lds_size
    .group_segment_fixed_size: 0
    .kernarg_segment_align: 8
    .kernarg_segment_size: 480
    .language:       OpenCL C
    .language_version:
      - 2
      - 0
    .max_flat_workgroup_size: 512
    .name:           _Z9hymba_fwd6Params
    .private_segment_fixed_size: 0
    .sgpr_count:     108
    .sgpr_spill_count: 145
    .symbol:         _Z9hymba_fwd6Params.kd
    .uniform_work_group_size: 1
    .uses_dynamic_stack: false
    .vgpr_count:     256
    .vgpr_spill_count: 0
    .wavefront_size: 64
